# conv item loop: the static s_setprio 1 goes to waves 0-3 instead of 4-7 (per-half comparison); GEMM raise unchanged
# baseline (speedup 1.0000x reference)
; #define LAS __attribute__((address_space(3)))
; DI bf16_t f2bf(float v) { return (bf16_t)(pk2(v, 0.f) & 0xffffu); }
; DI void conv_phase(PPtr p, int j, ldsp lds, int tid) {
;     ...
;     const int tok = tid >> 3, cgp = tid & 7;
;     for (int item = blockIdx.x; item < 256 * 12; item += gridDim.x) {
;         const int tt = item / 12, cb = item % 12;
;         const int t0 = tt * 64, b = t0 >> 12, s0 = t0 & 4095;
;         const int t = t0 + tok, s = s0 + tok;
;         u32x4 u[4][4];
; #pragma unroll
;         for (int k = 0; k < 4; ++k)
; #pragma unroll
;             for (int w = 0; w < 4; ++w) {
;                 const int ch0 = cb * 256 + (cgp + 8 * k) * 8;
;                 if (s - 3 + w >= 0) u[k][w] = *(const u32x4*)(zx + (size_t)(t - 3 + w) * ZXW + DIN + ch0);
;                 else u[k][w] = (u32x4){0u, 0u, 0u, 0u};
;             }
; #pragma unroll
;         for (int k = 0; k < 4; ++k) {
;             const int cl = (cgp + 8 * k) * 8, ch0 = cb * 256 + cl;
;     ...
;                 for (int i = 0; i < 8; ++i) *(LAS bf16_t*)(lds + (cl + i) * TPB + tok * 2) = f2bf(acc[i]);
;             }
;         }
;         if (cb < 10) {
;             __syncthreads();
; #pragma unroll
;             for (int k = 0; k < 4; ++k) { const int id = tid + 512 * k, row = id >> 3, ch = id & 7;
;                 const ldsp src = lds + row * TPB + ch * 16;
;                 u32x4 w; w.x = *(const LAS unsigned*)(src); w.y = *(const LAS unsigned*)(src + 4); w.z = *(const LAS unsigned*)(src + 8); w.w = *(const LAS unsigned*)(src + 12);
;                 bf16_t* dst = (cb < 8) ? xT + ((size_t)b * 2048 + cb * 256 + row) * SEQ + s0 + ch * 8 : BT + ((size_t)b * 512 + (cb - 8) * 256 + row) * SEQ + s0 + ch * 8;
.LBB0_510:
	v_readlane_b32 s0, v254, 13
	v_readlane_b32 s1, v254, 14
	s_andn2_b64 vcc, exec, s[0:1]
	s_cbranch_vccnz .LBB0_561
	v_readlane_b32 s0, v254, 51
	s_waitcnt lgkmcnt(0)
	s_add_u32 s2, s4, s0
	v_readlane_b32 s0, v254, 50
	s_addc_u32 s3, s5, s0
	v_readlane_b32 s0, v254, 53
	v_and_b32_e32 v2, 7, v42
	s_add_u32 s12, s6, s0
	v_readlane_b32 s0, v254, 52
	v_lshlrev_b32_e32 v72, 3, v2
	v_add_u32_e32 v7, 0x200, v42
	v_add_u32_e32 v8, 0x400, v42
	v_add_u32_e32 v9, 0x600, v42
	v_ashrrev_i32_e32 v70, 3, v42
	s_addc_u32 s13, s7, s0
	v_lshlrev_b32_e32 v0, 4, v2
	v_or_b32_e32 v5, 64, v72
	s_movk_i32 s0, 0x8c
	v_ashrrev_i32_e32 v74, 3, v7
	v_ashrrev_i32_e32 v76, 3, v8
	v_ashrrev_i32_e32 v78, 3, v9
	v_lshl_add_u32 v3, v70, 1, 0
	v_add_u32_e32 v4, 0, v0
	v_mul_u32_u24_e32 v2, 0x460, v2
	v_mul_u32_u24_e32 v5, 0x8c, v5
	v_mul_lo_u32 v6, v70, s0
	v_mul_lo_u32 v7, v74, s0
	v_mul_lo_u32 v8, v76, s0
	v_mul_lo_u32 v9, v78, s0
	v_mov_b32_e32 v73, v1
	v_ashrrev_i32_e32 v71, 31, v70
	v_ashrrev_i32_e32 v75, 31, v74
	v_ashrrev_i32_e32 v77, 31, v76
	v_ashrrev_i32_e32 v79, 31, v78
	v_lshl_add_u64 v[80:81], s[10:11], 0, v[0:1]
	s_lshl_b32 s18, s90, 8
	v_add_u32_e32 v84, v4, v6
	v_add_u32_e32 v85, v4, v7
	v_add_u32_e32 v86, v4, v8
	v_add_u32_e32 v87, v4, v9
	v_add_u32_e32 v88, v3, v2
	v_add_u32_e32 v89, v3, v5
	v_readlane_b32 s19, v254, 24
	v_readfirstlane_b32 s32, v153
	s_nop 3
	s_lshr_b32 s32, s32, 6
	s_cmp_ge_u32 s32, 4
	s_cbranch_scc1 .Lconv_prio_skip
	s_setprio 1
